# baseline (speedup 1.0000x reference)
.LBB0_799:
	s_or_b64 exec, exec, s[4:5]
	v_or_b32_e32 v130, s0, v147
	v_add_u32_e32 v132, v130, v148
	v_ashrrev_i32_e32 v133, 31, v132
	v_lshl_add_u64 v[134:135], v[132:133], 2, s[22:23]
	global_load_dword v130, v[134:135], off
	global_load_dword v200, v[134:135], off offset:512
	v_or_b32_e32 v138, 16, v132
	v_or_b32_e32 v136, 32, v132
	v_or_b32_e32 v134, 48, v132
	v_ashrrev_i32_e32 v139, 31, v138
	v_ashrrev_i32_e32 v137, 31, v136
	v_ashrrev_i32_e32 v135, 31, v134
	v_lshl_add_u64 v[140:141], v[138:139], 2, s[22:23]
	v_lshl_add_u64 v[142:143], v[136:137], 2, s[22:23]
	v_lshl_add_u64 v[150:151], v[134:135], 2, s[22:23]
	global_load_dword v148, v[140:141], off
	global_load_dword v147, v[142:143], off
	global_load_dword v144, v[150:151], off
	global_load_dword v201, v[140:141], off offset:512
	global_load_dword v202, v[142:143], off offset:512
	global_load_dword v203, v[150:151], off offset:512
	s_and_b32 s0, s10, 12
	s_cmp_eq_u32 s0, 4
	s_cselect_b64 s[10:11], -1, 0
	s_cmp_gt_u32 s12, 7
	s_cselect_b64 s[4:5], -1, 0
	s_cmp_lt_u32 s12, 8
	s_waitcnt vmcnt(0)
	v_fmamk_f32 v130, v130, 0x3a800000, v152
	v_mul_f32_e32 v140, 0x4b800000, v130
	v_cmp_gt_f32_e32 vcc, s94, v130
	s_nop 1
	v_cndmask_b32_e32 v130, v130, v140, vcc
	v_rsq_f32_e32 v130, v130
	s_nop 0
	v_mul_f32_e32 v140, 0x45800000, v130
	v_cndmask_b32_e32 v130, v130, v140, vcc
	v_mul_f32_e32 v140, 0x3e38aa3b, v130
	v_cndmask_b32_e64 v140, v130, v140, s[10:11]
	v_pk_mul_f32 v[122:123], v[122:123], v[140:141] op_sel_hi:[1,0]
	v_pk_mul_f32 v[142:143], v[124:125], v[140:141] op_sel_hi:[1,0]
	v_pk_mul_f32 v[124:125], v[126:127], v[140:141] op_sel_hi:[1,0]
	v_pk_mul_f32 v[128:129], v[128:129], v[140:141] op_sel_hi:[1,0]
	s_cbranch_scc1 .LBB0_801
	v_mul_f32_e32 v130, 0xbfb8aa3b, v142
	v_exp_f32_e32 v130, v130
	v_mul_f32_e32 v141, 0xbfb8aa3b, v143
	v_exp_f32_e32 v141, v141
	v_mul_f32_e32 v149, 0xbfb8aa3b, v125
	v_add_f32_e32 v130, 1.0, v130
	v_rcp_f32_e32 v150, v130
	v_add_f32_e32 v130, 1.0, v141
	v_mul_f32_e32 v141, 0xbfb8aa3b, v124
	v_exp_f32_e32 v141, v141
	v_exp_f32_e32 v149, v149
	v_rcp_f32_e32 v151, v130
	v_mul_f32_e32 v126, 0xbfb8aa3b, v122
	v_add_f32_e32 v130, 1.0, v141
	v_mul_f32_e32 v141, 0xbfb8aa3b, v128
	v_mul_f32_e32 v127, 0xbfb8aa3b, v123
	v_rcp_f32_e32 v154, v130
	v_add_f32_e32 v130, 1.0, v149
	v_exp_f32_e32 v141, v141
	v_mul_f32_e32 v149, 0xbfb8aa3b, v129
	v_exp_f32_e32 v126, v126
	v_exp_f32_e32 v127, v127
	v_exp_f32_e32 v149, v149
	v_rcp_f32_e32 v155, v130
	v_add_f32_e32 v130, 1.0, v141
	v_add_f32_e32 v126, 1.0, v126
	v_add_f32_e32 v127, 1.0, v127
	v_rcp_f32_e32 v156, v130
	v_add_f32_e32 v130, 1.0, v149
	v_rcp_f32_e32 v126, v126
	v_rcp_f32_e32 v127, v127
	v_rcp_f32_e32 v157, v130
	v_pk_mul_f32 v[142:143], v[142:143], v[150:151]
	v_pk_mul_f32 v[124:125], v[124:125], v[154:155]
	v_pk_mul_f32 v[122:123], v[122:123], v[126:127]
	v_pk_mul_f32 v[128:129], v[128:129], v[156:157]

.LBB0_879:
	v_add_u32_e32 v72, 0x80, v132
	v_ashrrev_i32_e32 v73, 31, v72
	v_lshl_add_u64 v[66:67], v[72:73], 2, s[22:23]
	v_mov_b32_e32 v81, v200
	v_add_u32_e32 v70, 0x90, v132
	v_add_u32_e32 v68, 0xa0, v132
	v_add_u32_e32 v66, 0xb0, v132
	v_ashrrev_i32_e32 v71, 31, v70
	v_ashrrev_i32_e32 v69, 31, v68
	v_ashrrev_i32_e32 v67, 31, v66
	v_lshl_add_u64 v[74:75], v[70:71], 2, s[22:23]
	v_lshl_add_u64 v[76:77], v[68:69], 2, s[22:23]
	v_lshl_add_u64 v[82:83], v[66:67], 2, s[22:23]
	v_mov_b32_e32 v80, v201
	v_mov_b32_e32 v79, v202
	v_mov_b32_e32 v78, v203
	s_and_b64 vcc, exec, s[6:7]
	s_nop 0
	v_fmamk_f32 v74, v81, 0x3a800000, v152
	v_mul_f32_e32 v75, 0x4b800000, v74
	v_cmp_gt_f32_e64 s[12:13], s94, v74
	s_nop 1
	v_cndmask_b32_e64 v74, v74, v75, s[12:13]
	v_rsq_f32_e32 v74, v74
	s_nop 0
	v_mul_f32_e32 v75, 0x45800000, v74
	v_cndmask_b32_e64 v74, v74, v75, s[12:13]
	v_mul_f32_e32 v75, 0x3e38aa3b, v74
	v_cndmask_b32_e64 v74, v74, v75, s[10:11]
	v_pk_mul_f32 v[58:59], v[58:59], v[74:75] op_sel_hi:[1,0]
	v_pk_mul_f32 v[76:77], v[60:61], v[74:75] op_sel_hi:[1,0]
	v_pk_mul_f32 v[60:61], v[62:63], v[74:75] op_sel_hi:[1,0]
	v_pk_mul_f32 v[64:65], v[64:65], v[74:75] op_sel_hi:[1,0]
	s_cbranch_vccnz .LBB0_881
	v_mul_f32_e32 v75, 0xbfb8aa3b, v76
	v_exp_f32_e32 v75, v75
	v_mul_f32_e32 v81, 0xbfb8aa3b, v77
	v_exp_f32_e32 v81, v81
	v_mul_f32_e32 v83, 0xbfb8aa3b, v61
	v_add_f32_e32 v75, 1.0, v75
	v_rcp_f32_e32 v82, v75
	v_add_f32_e32 v75, 1.0, v81
	v_mul_f32_e32 v81, 0xbfb8aa3b, v60
	v_exp_f32_e32 v81, v81
	v_exp_f32_e32 v85, v83
	v_rcp_f32_e32 v83, v75
	v_mul_f32_e32 v62, 0xbfb8aa3b, v58
	v_add_f32_e32 v75, 1.0, v81
	v_mul_f32_e32 v81, 0xbfb8aa3b, v64
	v_mul_f32_e32 v63, 0xbfb8aa3b, v59
	v_rcp_f32_e32 v84, v75
	v_add_f32_e32 v75, 1.0, v85
	v_exp_f32_e32 v81, v81
	v_mul_f32_e32 v85, 0xbfb8aa3b, v65
	v_exp_f32_e32 v62, v62
	v_exp_f32_e32 v63, v63
	v_exp_f32_e32 v87, v85
	v_rcp_f32_e32 v85, v75
	v_add_f32_e32 v75, 1.0, v81
	v_add_f32_e32 v62, 1.0, v62
	v_add_f32_e32 v63, 1.0, v63
	v_rcp_f32_e32 v86, v75
	v_add_f32_e32 v75, 1.0, v87
	v_rcp_f32_e32 v62, v62
	v_rcp_f32_e32 v63, v63
	v_rcp_f32_e32 v87, v75
	v_pk_mul_f32 v[76:77], v[76:77], v[82:83]
	v_pk_mul_f32 v[60:61], v[60:61], v[84:85]
	v_pk_mul_f32 v[58:59], v[58:59], v[62:63]
	v_pk_mul_f32 v[64:65], v[64:65], v[86:87]

.LBB0_899:
	s_nop 0
	s_nop 0
	v_fmamk_f32 v50, v80, 0x3a800000, v152
	v_mul_f32_e32 v51, 0x4b800000, v50
	v_cmp_gt_f32_e32 vcc, s94, v50
	s_nop 1
	v_cndmask_b32_e32 v50, v50, v51, vcc
	v_rsq_f32_e32 v50, v50
	s_nop 0
	v_mul_f32_e32 v51, 0x45800000, v50
	v_cndmask_b32_e32 v50, v50, v51, vcc
	v_mul_f32_e32 v51, 0x3e38aa3b, v50
	v_cndmask_b32_e64 v50, v50, v51, s[10:11]
	v_pk_mul_f32 v[52:53], v[46:47], v[50:51] op_sel_hi:[1,0]
	v_pk_mul_f32 v[54:55], v[48:49], v[50:51] op_sel_hi:[1,0]
	v_pk_mul_f32 v[48:49], v[42:43], v[50:51] op_sel_hi:[1,0]
	s_and_b64 vcc, exec, s[6:7]
	v_pk_mul_f32 v[56:57], v[44:45], v[50:51] op_sel_hi:[1,0]
	s_cbranch_vccnz .LBB0_901
	v_mul_f32_e32 v51, 0xbfb8aa3b, v56
	v_mul_f32_e32 v42, 0xbfb8aa3b, v52
	v_mul_f32_e32 v43, 0xbfb8aa3b, v53
	v_mul_f32_e32 v44, 0xbfb8aa3b, v54
	v_mul_f32_e32 v45, 0xbfb8aa3b, v55
	v_mul_f32_e32 v46, 0xbfb8aa3b, v48
	v_mul_f32_e32 v47, 0xbfb8aa3b, v49
	v_exp_f32_e32 v51, v51
	v_mul_f32_e32 v58, 0xbfb8aa3b, v57
	v_exp_f32_e32 v42, v42
	v_exp_f32_e32 v43, v43
	v_exp_f32_e32 v44, v44
	v_exp_f32_e32 v45, v45
	v_exp_f32_e32 v46, v46
	v_exp_f32_e32 v47, v47
	v_exp_f32_e32 v59, v58
	v_add_f32_e32 v51, 1.0, v51
	v_add_f32_e32 v42, 1.0, v42
	v_add_f32_e32 v43, 1.0, v43
	v_add_f32_e32 v44, 1.0, v44
	v_add_f32_e32 v45, 1.0, v45
	v_add_f32_e32 v46, 1.0, v46
	v_add_f32_e32 v47, 1.0, v47
	v_rcp_f32_e32 v58, v51
	v_add_f32_e32 v51, 1.0, v59
	v_rcp_f32_e32 v42, v42
	v_rcp_f32_e32 v43, v43
	v_rcp_f32_e32 v44, v44
	v_rcp_f32_e32 v45, v45
	v_rcp_f32_e32 v46, v46
	v_rcp_f32_e32 v47, v47
	v_rcp_f32_e32 v59, v51
	v_pk_mul_f32 v[52:53], v[52:53], v[42:43]
	v_pk_mul_f32 v[54:55], v[54:55], v[44:45]
	v_pk_mul_f32 v[48:49], v[48:49], v[46:47]
	v_pk_mul_f32 v[56:57], v[56:57], v[58:59]

.LBB0_919:
	s_nop 0
	s_nop 0
	v_fmamk_f32 v34, v79, 0x3a800000, v152
	v_mul_f32_e32 v35, 0x4b800000, v34
	v_cmp_gt_f32_e32 vcc, s94, v34
	s_nop 1
	v_cndmask_b32_e32 v34, v34, v35, vcc
	v_rsq_f32_e32 v34, v34
	s_nop 0
	v_mul_f32_e32 v35, 0x45800000, v34
	v_cndmask_b32_e32 v34, v34, v35, vcc
	v_mul_f32_e32 v35, 0x3e38aa3b, v34
	v_cndmask_b32_e64 v34, v34, v35, s[10:11]
	v_pk_mul_f32 v[36:37], v[30:31], v[34:35] op_sel_hi:[1,0]
	v_pk_mul_f32 v[38:39], v[32:33], v[34:35] op_sel_hi:[1,0]
	v_pk_mul_f32 v[32:33], v[26:27], v[34:35] op_sel_hi:[1,0]
	s_and_b64 vcc, exec, s[6:7]
	v_pk_mul_f32 v[40:41], v[28:29], v[34:35] op_sel_hi:[1,0]
	s_cbranch_vccnz .LBB0_921
	v_mul_f32_e32 v35, 0xbfb8aa3b, v40
	v_mul_f32_e32 v26, 0xbfb8aa3b, v36
	v_mul_f32_e32 v27, 0xbfb8aa3b, v37
	v_mul_f32_e32 v28, 0xbfb8aa3b, v38
	v_mul_f32_e32 v29, 0xbfb8aa3b, v39
	v_mul_f32_e32 v30, 0xbfb8aa3b, v32
	v_mul_f32_e32 v31, 0xbfb8aa3b, v33
	v_exp_f32_e32 v35, v35
	v_mul_f32_e32 v42, 0xbfb8aa3b, v41
	v_exp_f32_e32 v26, v26
	v_exp_f32_e32 v27, v27
	v_exp_f32_e32 v28, v28
	v_exp_f32_e32 v29, v29
	v_exp_f32_e32 v30, v30
	v_exp_f32_e32 v31, v31
	v_exp_f32_e32 v43, v42
	v_add_f32_e32 v35, 1.0, v35
	v_add_f32_e32 v26, 1.0, v26
	v_add_f32_e32 v27, 1.0, v27
	v_add_f32_e32 v28, 1.0, v28
	v_add_f32_e32 v29, 1.0, v29
	v_add_f32_e32 v30, 1.0, v30
	v_add_f32_e32 v31, 1.0, v31
	v_rcp_f32_e32 v42, v35
	v_add_f32_e32 v35, 1.0, v43
	v_rcp_f32_e32 v26, v26
	v_rcp_f32_e32 v27, v27
	v_rcp_f32_e32 v28, v28
	v_rcp_f32_e32 v29, v29
	v_rcp_f32_e32 v30, v30
	v_rcp_f32_e32 v31, v31
	v_rcp_f32_e32 v43, v35
	v_pk_mul_f32 v[36:37], v[36:37], v[26:27]
	v_pk_mul_f32 v[38:39], v[38:39], v[28:29]
	v_pk_mul_f32 v[32:33], v[32:33], v[30:31]
	v_pk_mul_f32 v[40:41], v[40:41], v[42:43]

.LBB0_939:
	s_nop 0
	s_nop 0
	v_fmamk_f32 v18, v78, 0x3a800000, v152
	v_mul_f32_e32 v19, 0x4b800000, v18
	v_cmp_gt_f32_e32 vcc, s94, v18
	s_nop 1
	v_cndmask_b32_e32 v18, v18, v19, vcc
	v_rsq_f32_e32 v18, v18
	s_nop 0
	v_mul_f32_e32 v19, 0x45800000, v18
	v_cndmask_b32_e32 v18, v18, v19, vcc
	v_mul_f32_e32 v19, 0x3e38aa3b, v18
	v_cndmask_b32_e64 v18, v18, v19, s[10:11]
	v_pk_mul_f32 v[20:21], v[14:15], v[18:19] op_sel_hi:[1,0]
	v_pk_mul_f32 v[22:23], v[16:17], v[18:19] op_sel_hi:[1,0]
	v_pk_mul_f32 v[16:17], v[10:11], v[18:19] op_sel_hi:[1,0]
	s_and_b64 vcc, exec, s[6:7]
	v_pk_mul_f32 v[24:25], v[12:13], v[18:19] op_sel_hi:[1,0]
	s_cbranch_vccnz .LBB0_941
	v_mul_f32_e32 v19, 0xbfb8aa3b, v24
	v_mul_f32_e32 v10, 0xbfb8aa3b, v20
	v_mul_f32_e32 v11, 0xbfb8aa3b, v21
	v_mul_f32_e32 v12, 0xbfb8aa3b, v22
	v_mul_f32_e32 v13, 0xbfb8aa3b, v23
	v_mul_f32_e32 v14, 0xbfb8aa3b, v16
	v_mul_f32_e32 v15, 0xbfb8aa3b, v17
	v_exp_f32_e32 v19, v19
	v_mul_f32_e32 v26, 0xbfb8aa3b, v25
	v_exp_f32_e32 v10, v10
	v_exp_f32_e32 v11, v11
	v_exp_f32_e32 v12, v12
	v_exp_f32_e32 v13, v13
	v_exp_f32_e32 v14, v14
	v_exp_f32_e32 v15, v15
	v_exp_f32_e32 v27, v26
	v_add_f32_e32 v19, 1.0, v19
	v_add_f32_e32 v10, 1.0, v10
	v_add_f32_e32 v11, 1.0, v11
	v_add_f32_e32 v12, 1.0, v12
	v_add_f32_e32 v13, 1.0, v13
	v_add_f32_e32 v14, 1.0, v14
	v_add_f32_e32 v15, 1.0, v15
	v_rcp_f32_e32 v26, v19
	v_add_f32_e32 v19, 1.0, v27
	v_rcp_f32_e32 v10, v10
	v_rcp_f32_e32 v11, v11
	v_rcp_f32_e32 v12, v12
	v_rcp_f32_e32 v13, v13
	v_rcp_f32_e32 v14, v14
	v_rcp_f32_e32 v15, v15
	v_rcp_f32_e32 v27, v19
	v_pk_mul_f32 v[20:21], v[20:21], v[10:11]
	v_pk_mul_f32 v[22:23], v[22:23], v[12:13]
	v_pk_mul_f32 v[16:17], v[16:17], v[14:15]
	v_pk_mul_f32 v[24:25], v[24:25], v[26:27]
